# prep3a fast path: f32->bf16 RNE via v_cvt_pk_bf16_f32 instead of the bfe+add3 bit trick (44 sites)
# baseline (speedup 1.0000x reference)
.LBB0_693:
	v_readlane_b32 s40, v254, 24
	s_andn2_b64 vcc, exec, s[0:1]
	v_readlane_b32 s41, v254, 25
	s_cbranch_vccnz .LBB0_786
	s_waitcnt lgkmcnt(0)
	v_readlane_b32 s2, v254, 8
	v_readlane_b32 s3, v254, 9
	s_mov_b64 s[0:1], -1
	s_and_b64 vcc, exec, s[2:3]
	s_movk_i32 s19, 0xfff
	s_cbranch_vccz .LBB0_767
	v_readlane_b32 s2, v254, 12
	v_readlane_b32 s3, v254, 13
	v_readlane_b32 s50, v254, 22
	s_and_b64 vcc, exec, s[2:3]
	s_movk_i32 s17, 0x4000
	s_mov_b32 s18, 0xbfb8aa3b
	s_movk_i32 s27, 0x1a00
	s_mov_b32 s40, 0x40000
	s_mov_b32 s41, 0x3ffff
	s_mov_b32 s43, 0x100000
	s_mov_b32 s44, 0xfffff
	s_mov_b32 s48, 0x3f317217
	s_mov_b32 s49, 0x7f800000
	v_readlane_b32 s51, v254, 23
	s_cbranch_vccz .LBB0_756
	v_readlane_b32 s2, v254, 14
	v_readlane_b32 s3, v254, 15
	s_and_b64 vcc, exec, s[2:3]
	s_mov_b32 s16, 0xffff
	s_mov_b32 s42, 0x7ffff
	s_mov_b32 s47, 0x7060302
	s_cbranch_vccz .LBB0_720
	v_mov_b32_e32 v1, v0
	v_mov_b32_e32 v2, v0
	s_mov_b32 s0, s87
	v_ashrrev_i32_e32 v2, 6, v2
	s_nop 0
	v_lshl_add_u32 v4, s0, 3, v2
	s_movk_i32 s0, 0x2000
	v_cmp_gt_i32_e32 vcc, s0, v4
	s_and_saveexec_b64 s[0:1], vcc
	s_cbranch_execz .LBB0_711
	v_and_b32_e32 v6, 63, v1
	v_and_b32_e32 v1, 64, v223
	v_add_u32_e32 v5, 64, v1
	v_xor_b32_e32 v1, 32, v223
	v_cmp_lt_i32_e32 vcc, v1, v5
	v_xor_b32_e32 v7, 16, v223
	v_xor_b32_e32 v12, 8, v223
	v_cndmask_b32_e32 v1, v223, v1, vcc
	v_cmp_lt_i32_e32 vcc, v7, v5
	s_load_dword s2, s[20:21], 0x0
	s_load_dwordx2 s[6:7], s[30:31], 0x130
	s_load_dwordx2 s[8:9], s[30:31], 0x148
	v_cndmask_b32_e32 v7, v223, v7, vcc
	v_cmp_lt_i32_e32 vcc, v12, v5
	v_lshlrev_b32_e32 v14, 2, v6
	v_mov_b32_e32 v15, v3
	v_cndmask_b32_e32 v12, v223, v12, vcc
	v_lshlrev_b32_e32 v34, 2, v12
	v_xor_b32_e32 v12, 4, v223
	v_cmp_lt_i32_e32 vcc, v12, v5
	v_lshlrev_b32_e32 v2, 1, v6
	v_lshl_add_u64 v[8:9], s[36:37], 0, v[2:3]
	v_cndmask_b32_e32 v12, v223, v12, vcc
	v_lshlrev_b32_e32 v35, 2, v12
	v_xor_b32_e32 v12, 2, v223
	v_cmp_lt_i32_e32 vcc, v12, v5
	v_lshl_add_u64 v[10:11], s[76:77], 0, v[2:3]
	v_cmp_gt_u32_e64 s[4:5], 32, v6
	v_cndmask_b32_e32 v12, v223, v12, vcc
	v_lshlrev_b32_e32 v37, 2, v12
	v_xor_b32_e32 v12, 1, v223
	v_cmp_lt_i32_e32 vcc, v12, v5
	s_waitcnt lgkmcnt(0)
	s_lshl_b32 s2, s2, 3
	v_lshlrev_b32_e32 v1, 2, v1
	v_cndmask_b32_e32 v5, v223, v12, vcc
	v_lshl_add_u64 v[12:13], s[6:7], 0, v[14:15]
	v_readlane_b32 s6, v254, 20
	v_readlane_b32 s7, v254, 21
	v_lshlrev_b32_e32 v7, 2, v7
	v_lshlrev_b32_e32 v38, 2, v5
	v_lshl_add_u64 v[14:15], s[8:9], 0, v[14:15]
	v_lshl_add_u64 v[16:17], s[34:35], 0, v[2:3]
	v_lshl_add_u64 v[18:19], s[6:7], 0, v[2:3]
	s_mov_b64 s[6:7], 0
	s_cmp_eq_u32 s2, 0x800
	s_cbranch_scc0 .LBB0_700
	v_readfirstlane_b32 s3, v4
	s_cmp_lt_u32 s3, 0x800
	s_cbranch_scc0 .LBB0_700
	s_load_dwordx2 s[10:11], s[30:31], 0x170
	global_load_dword v124, v[12:13], off
	global_load_dword v125, v[12:13], off offset:256
	global_load_dword v126, v[12:13], off offset:512
	global_load_dword v127, v[12:13], off offset:768
	global_load_dword v128, v[12:13], off offset:1024
	global_load_dword v129, v[12:13], off offset:1280
	global_load_dword v130, v[14:15], off
	global_load_dword v131, v[14:15], off offset:256
	global_load_dword v132, v[14:15], off offset:512
	global_load_dword v133, v[14:15], off offset:768
	v_mov_b32_e32 v134, v4
	s_movk_i32 s3, 0x600
	v_mad_i64_i32 v[136:137], s[8:9], v134, s3, v[16:17]
	v_mad_i64_i32 v[142:143], s[8:9], v134, s3, v[18:19]
	global_load_ushort v80, v[136:137], off
	global_load_ushort v81, v[136:137], off offset:128
	global_load_ushort v82, v[136:137], off offset:256
	global_load_ushort v83, v[136:137], off offset:384
	global_load_ushort v84, v[136:137], off offset:512
	global_load_ushort v85, v[136:137], off offset:640
	global_load_ushort v86, v[136:137], off offset:768
	global_load_ushort v87, v[136:137], off offset:896
	global_load_ushort v88, v[136:137], off offset:1024
	global_load_ushort v89, v[136:137], off offset:1152
	global_load_ushort v90, v[136:137], off offset:1280
	global_load_ushort v91, v[142:143], off
	global_load_ushort v92, v[142:143], off offset:128
	global_load_ushort v93, v[142:143], off offset:256
	global_load_ushort v94, v[142:143], off offset:384
	global_load_ushort v95, v[142:143], off offset:512
	global_load_ushort v96, v[142:143], off offset:640
	global_load_ushort v97, v[142:143], off offset:768
	global_load_ushort v98, v[142:143], off offset:896
	global_load_ushort v99, v[142:143], off offset:1024
	global_load_ushort v100, v[142:143], off offset:1152
	global_load_ushort v101, v[142:143], off offset:1280
	v_add_u32_e32 v135, 0x800, v4
	s_movk_i32 s3, 0x600
	v_mad_i64_i32 v[138:139], s[8:9], v135, s3, v[16:17]
	v_mad_i64_i32 v[144:145], s[8:9], v135, s3, v[18:19]
	global_load_ushort v102, v[138:139], off
	global_load_ushort v103, v[138:139], off offset:128
	global_load_ushort v104, v[138:139], off offset:256
	global_load_ushort v105, v[138:139], off offset:384
	global_load_ushort v106, v[138:139], off offset:512
	global_load_ushort v107, v[138:139], off offset:640
	global_load_ushort v108, v[138:139], off offset:768
	global_load_ushort v109, v[138:139], off offset:896
	global_load_ushort v110, v[138:139], off offset:1024
	global_load_ushort v111, v[138:139], off offset:1152
	global_load_ushort v112, v[138:139], off offset:1280
	global_load_ushort v113, v[144:145], off
	global_load_ushort v114, v[144:145], off offset:128
	global_load_ushort v115, v[144:145], off offset:256
	global_load_ushort v116, v[144:145], off offset:384
	global_load_ushort v117, v[144:145], off offset:512
	global_load_ushort v118, v[144:145], off offset:640
	global_load_ushort v119, v[144:145], off offset:768
	global_load_ushort v120, v[144:145], off offset:896
	global_load_ushort v121, v[144:145], off offset:1024
	global_load_ushort v122, v[144:145], off offset:1152
	global_load_ushort v123, v[144:145], off offset:1280
	s_waitcnt vmcnt(0)
	v_add_u32_e32 v248, 0x1000, v4
	s_movk_i32 s3, 0x600
	v_mad_i64_i32 v[250:251], s[8:9], v248, s3, v[16:17]
	v_mad_i64_i32 v[152:153], s[8:9], v248, s3, v[18:19]
	global_load_ushort v188, v[250:251], off
	global_load_ushort v189, v[250:251], off offset:128
	global_load_ushort v190, v[250:251], off offset:256
	global_load_ushort v191, v[250:251], off offset:384
	global_load_ushort v192, v[250:251], off offset:512
	global_load_ushort v193, v[250:251], off offset:640
	global_load_ushort v194, v[250:251], off offset:768
	global_load_ushort v195, v[250:251], off offset:896
	global_load_ushort v196, v[250:251], off offset:1024
	global_load_ushort v197, v[250:251], off offset:1152
	global_load_ushort v198, v[250:251], off offset:1280
	global_load_ushort v199, v[152:153], off
	global_load_ushort v200, v[152:153], off offset:128
	global_load_ushort v201, v[152:153], off offset:256
	global_load_ushort v202, v[152:153], off offset:384
	global_load_ushort v203, v[152:153], off offset:512
	global_load_ushort v204, v[152:153], off offset:640
	global_load_ushort v205, v[152:153], off offset:768
	global_load_ushort v206, v[152:153], off offset:896
	global_load_ushort v207, v[152:153], off offset:1024
	global_load_ushort v208, v[152:153], off offset:1152
	global_load_ushort v209, v[152:153], off offset:1280
	v_add_u32_e32 v249, 0x1800, v4
	s_movk_i32 s3, 0x600
	v_mad_i64_i32 v[252:253], s[8:9], v249, s3, v[16:17]
	v_mad_i64_i32 v[154:155], s[8:9], v249, s3, v[18:19]
	global_load_ushort v210, v[252:253], off
	global_load_ushort v211, v[252:253], off offset:128
	global_load_ushort v212, v[252:253], off offset:256
	global_load_ushort v213, v[252:253], off offset:384
	global_load_ushort v214, v[252:253], off offset:512
	global_load_ushort v215, v[252:253], off offset:640
	global_load_ushort v216, v[252:253], off offset:768
	global_load_ushort v217, v[252:253], off offset:896
	global_load_ushort v234, v[252:253], off offset:1024
	global_load_ushort v235, v[252:253], off offset:1152
	global_load_ushort v236, v[252:253], off offset:1280
	global_load_ushort v237, v[154:155], off
	global_load_ushort v238, v[154:155], off offset:128
	global_load_ushort v239, v[154:155], off offset:256
	global_load_ushort v240, v[154:155], off offset:384
	global_load_ushort v241, v[154:155], off offset:512
	global_load_ushort v242, v[154:155], off offset:640
	global_load_ushort v243, v[154:155], off offset:768
	global_load_ushort v244, v[154:155], off offset:896
	global_load_ushort v245, v[154:155], off offset:1024
	global_load_ushort v246, v[154:155], off offset:1152
	global_load_ushort v247, v[154:155], off offset:1280
	v_lshlrev_b32_e32 v80, 16, v80
	v_lshlrev_b32_e32 v91, 16, v91
	v_add_f32_e32 v80, v80, v91
	v_lshlrev_b32_e32 v81, 16, v81
	v_lshlrev_b32_e32 v92, 16, v92
	v_add_f32_e32 v81, v81, v92
	v_lshlrev_b32_e32 v82, 16, v82
	v_lshlrev_b32_e32 v93, 16, v93
	v_add_f32_e32 v82, v82, v93
	v_lshlrev_b32_e32 v83, 16, v83
	v_lshlrev_b32_e32 v94, 16, v94
	v_add_f32_e32 v83, v83, v94
	v_lshlrev_b32_e32 v84, 16, v84
	v_lshlrev_b32_e32 v95, 16, v95
	v_add_f32_e32 v84, v84, v95
	v_lshlrev_b32_e32 v85, 16, v85
	v_lshlrev_b32_e32 v96, 16, v96
	v_add_f32_e32 v85, v85, v96
	v_lshlrev_b32_e32 v86, 16, v86
	v_lshlrev_b32_e32 v97, 16, v97
	v_add_f32_e32 v86, v86, v97
	v_lshlrev_b32_e32 v87, 16, v87
	v_lshlrev_b32_e32 v98, 16, v98
	v_add_f32_e32 v87, v87, v98
	v_lshlrev_b32_e32 v88, 16, v88
	v_lshlrev_b32_e32 v99, 16, v99
	v_add_f32_e32 v88, v88, v99
	v_lshlrev_b32_e32 v89, 16, v89
	v_lshlrev_b32_e32 v100, 16, v100
	v_add_f32_e32 v89, v89, v100
	v_lshlrev_b32_e32 v90, 16, v90
	v_lshlrev_b32_e32 v101, 16, v101
	v_add_f32_e32 v90, v101, v90
	v_mul_f32_e32 v146, v81, v81
	v_fmac_f32_e32 v146, v80, v80
	v_mul_f32_e32 v147, v82, v82
	v_add_f32_e32 v146, v146, v147
	v_mul_f32_e32 v147, v83, v83
	v_add_f32_e32 v146, v146, v147
	v_mul_f32_e32 v147, v84, v84
	v_add_f32_e32 v146, v146, v147
	v_mul_f32_e32 v147, v85, v85
	v_add_f32_e32 v146, v146, v147
	s_nop 1
	v_add_f32_dpp v146, v146, v146 quad_perm:[1,0,3,2] row_mask:0xf bank_mask:0xf
	s_nop 1
	v_add_f32_dpp v146, v146, v146 quad_perm:[2,3,0,1] row_mask:0xf bank_mask:0xf
	s_nop 1
	v_add_f32_dpp v146, v146, v146 row_half_mirror row_mask:0xf bank_mask:0xf
	s_nop 1
	v_add_f32_dpp v146, v146, v146 row_mirror row_mask:0xf bank_mask:0xf
	v_mov_b32_e32 v147, v146
	s_nop 1
	v_permlane16_swap_b32 v146, v147
	v_add_f32_e32 v146, v146, v147
	v_mov_b32_e32 v147, v146
	s_nop 1
	v_permlane32_swap_b32 v146, v147
	v_add_f32_e32 v146, v146, v147
	v_fmamk_f32 v146, v146, 0x3b2aaaab, v218
	v_cmp_gt_f32_e32 vcc, s71, v146
	v_mul_f32_e32 v147, 0x4b800000, v146
	s_nop 0
	v_cndmask_b32_e32 v146, v146, v147, vcc
	v_rsq_f32_e32 v146, v146
	s_nop 0
	v_mul_f32_e32 v147, 0x45800000, v146
	v_cndmask_b32_e32 v146, v146, v147, vcc
	v_mad_i64_i32 v[148:149], s[8:9], v134, s70, v[8:9]
	v_mul_f32_e32 v147, v80, v146
	v_mul_f32_e32 v147, v124, v147
	v_cvt_pk_bf16_f32 v147, v147, v147
	global_store_short_d16_hi v[148:149], v147, off
	v_mul_f32_e32 v147, v81, v146
	v_mul_f32_e32 v147, v125, v147
	v_cvt_pk_bf16_f32 v147, v147, v147
	global_store_short_d16_hi v[148:149], v147, off offset:128
	v_mul_f32_e32 v147, v82, v146
	v_mul_f32_e32 v147, v126, v147
	v_cvt_pk_bf16_f32 v147, v147, v147
	global_store_short_d16_hi v[148:149], v147, off offset:256
	v_mul_f32_e32 v147, v83, v146
	v_mul_f32_e32 v147, v127, v147
	v_cvt_pk_bf16_f32 v147, v147, v147
	global_store_short_d16_hi v[148:149], v147, off offset:384
	v_mul_f32_e32 v147, v84, v146
	v_mul_f32_e32 v147, v128, v147
	v_cvt_pk_bf16_f32 v147, v147, v147
	global_store_short_d16_hi v[148:149], v147, off offset:512
	v_mul_f32_e32 v147, v85, v146
	v_mul_f32_e32 v147, v129, v147
	v_cvt_pk_bf16_f32 v147, v147, v147
	global_store_short_d16_hi v[148:149], v147, off offset:640
	v_mul_f32_e32 v146, v86, v86
	v_mul_f32_e32 v147, v87, v87
	v_add_f32_e32 v146, v146, v147
	v_mul_f32_e32 v147, v88, v88
	v_add_f32_e32 v146, v146, v147
	v_mul_f32_e32 v147, v89, v89
	v_add_f32_e32 v146, v146, v147
	s_nop 1
	v_add_f32_dpp v146, v146, v146 quad_perm:[1,0,3,2] row_mask:0xf bank_mask:0xf
	s_nop 1
	v_add_f32_dpp v146, v146, v146 quad_perm:[2,3,0,1] row_mask:0xf bank_mask:0xf
	s_nop 1
	v_add_f32_dpp v146, v146, v146 row_half_mirror row_mask:0xf bank_mask:0xf
	s_nop 1
	v_add_f32_dpp v146, v146, v146 row_mirror row_mask:0xf bank_mask:0xf
	v_mov_b32_e32 v147, v146
	s_nop 1
	v_permlane16_swap_b32 v146, v147
	v_add_f32_e32 v146, v146, v147
	v_mov_b32_e32 v147, v146
	s_nop 1
	v_permlane32_swap_b32 v146, v147
	v_add_f32_e32 v146, v146, v147
	v_fmamk_f32 v146, v146, 0x3b800000, v218
	v_cmp_gt_f32_e32 vcc, s71, v146
	v_mul_f32_e32 v147, 0x4b800000, v146
	s_nop 0
	v_cndmask_b32_e32 v146, v146, v147, vcc
	v_rsq_f32_e32 v146, v146
	s_nop 0
	v_mul_f32_e32 v147, 0x45800000, v146
	v_cndmask_b32_e32 v146, v146, v147, vcc
	v_ashrrev_i32_e32 v151, 31, v134
	v_mov_b32_e32 v150, v134
	v_lshlrev_b64 v[148:149], 9, v[150:151]
	v_lshl_add_u64 v[148:149], v[10:11], 0, v[148:149]
	v_lshlrev_b64 v[152:153], 10, v[150:151]
	s_waitcnt lgkmcnt(0)
	v_lshl_add_u64 v[152:153], s[10:11], 0, v[152:153]
	v_lshlrev_b32_e32 v154, 2, v6
	v_mov_b32_e32 v155, v3
	v_lshl_add_u64 v[154:155], v[152:153], 0, v[154:155]
	s_mov_b64 s[8:9], 0x7000000
	v_lshl_add_u64 v[154:155], v[154:155], 0, s[8:9]
	v_mul_f32_e32 v147, v86, v146
	v_mul_f32_e32 v147, v130, v147
	v_cvt_pk_bf16_f32 v150, v147, v147
	global_store_short_d16_hi v[148:149], v150, off
	global_store_dword v[154:155], v147, off
	v_mul_f32_e32 v147, v87, v146
	v_mul_f32_e32 v147, v131, v147
	v_cvt_pk_bf16_f32 v150, v147, v147
	global_store_short_d16_hi v[148:149], v150, off offset:128
	global_store_dword v[154:155], v147, off offset:256
	v_mul_f32_e32 v147, v88, v146
	v_mul_f32_e32 v147, v132, v147
	v_cvt_pk_bf16_f32 v150, v147, v147
	global_store_short_d16_hi v[148:149], v150, off offset:256
	global_store_dword v[154:155], v147, off offset:512
	v_mul_f32_e32 v147, v89, v146
	v_mul_f32_e32 v147, v133, v147
	v_cvt_pk_bf16_f32 v150, v147, v147
	global_store_short_d16_hi v[148:149], v150, off offset:384
	global_store_dword v[154:155], v147, off offset:768
	s_and_saveexec_b64 s[8:9], s[4:5]
	v_cvt_pk_bf16_f32 v147, v90, v90
	global_store_short_d16_hi v[136:137], v147, off offset:1280
	s_movk_i32 s3, 0xfc80
	v_mad_i64_i32 v[148:149], s[12:13], v134, s3, v[152:153]
	v_lshlrev_b32_e32 v150, 2, v6
	v_mov_b32_e32 v151, v3
	v_lshl_add_u64 v[148:149], v[148:149], 0, v[150:151]
	v_add_co_u32_e32 v148, vcc, 0x7400000, v148
	s_nop 1
	v_addc_co_u32_e32 v149, vcc, 0, v149, vcc
	global_store_dword v[148:149], v90, off
	s_or_b64 exec, exec, s[8:9]
	v_lshlrev_b32_e32 v102, 16, v102
	v_lshlrev_b32_e32 v113, 16, v113
	v_add_f32_e32 v102, v102, v113
	v_lshlrev_b32_e32 v103, 16, v103
	v_lshlrev_b32_e32 v114, 16, v114
	v_add_f32_e32 v103, v103, v114
	v_lshlrev_b32_e32 v104, 16, v104
	v_lshlrev_b32_e32 v115, 16, v115
	v_add_f32_e32 v104, v104, v115
	v_lshlrev_b32_e32 v105, 16, v105
	v_lshlrev_b32_e32 v116, 16, v116
	v_add_f32_e32 v105, v105, v116
	v_lshlrev_b32_e32 v106, 16, v106
	v_lshlrev_b32_e32 v117, 16, v117
	v_add_f32_e32 v106, v106, v117
	v_lshlrev_b32_e32 v107, 16, v107
	v_lshlrev_b32_e32 v118, 16, v118
	v_add_f32_e32 v107, v107, v118
	v_lshlrev_b32_e32 v108, 16, v108
	v_lshlrev_b32_e32 v119, 16, v119
	v_add_f32_e32 v108, v108, v119
	v_lshlrev_b32_e32 v109, 16, v109
	v_lshlrev_b32_e32 v120, 16, v120
	v_add_f32_e32 v109, v109, v120
	v_lshlrev_b32_e32 v110, 16, v110
	v_lshlrev_b32_e32 v121, 16, v121
	v_add_f32_e32 v110, v110, v121
	v_lshlrev_b32_e32 v111, 16, v111
	v_lshlrev_b32_e32 v122, 16, v122
	v_add_f32_e32 v111, v111, v122
	v_lshlrev_b32_e32 v112, 16, v112
	v_lshlrev_b32_e32 v123, 16, v123
	v_add_f32_e32 v112, v123, v112
	v_mul_f32_e32 v146, v103, v103
	v_fmac_f32_e32 v146, v102, v102
	v_mul_f32_e32 v147, v104, v104
	v_add_f32_e32 v146, v146, v147
	v_mul_f32_e32 v147, v105, v105
	v_add_f32_e32 v146, v146, v147
	v_mul_f32_e32 v147, v106, v106
	v_add_f32_e32 v146, v146, v147
	v_mul_f32_e32 v147, v107, v107
	v_add_f32_e32 v146, v146, v147
	s_nop 1
	v_add_f32_dpp v146, v146, v146 quad_perm:[1,0,3,2] row_mask:0xf bank_mask:0xf
	s_nop 1
	v_add_f32_dpp v146, v146, v146 quad_perm:[2,3,0,1] row_mask:0xf bank_mask:0xf
	s_nop 1
	v_add_f32_dpp v146, v146, v146 row_half_mirror row_mask:0xf bank_mask:0xf
	s_nop 1
	v_add_f32_dpp v146, v146, v146 row_mirror row_mask:0xf bank_mask:0xf
	v_mov_b32_e32 v147, v146
	s_nop 1
	v_permlane16_swap_b32 v146, v147
	v_add_f32_e32 v146, v146, v147
	v_mov_b32_e32 v147, v146
	s_nop 1
	v_permlane32_swap_b32 v146, v147
	v_add_f32_e32 v146, v146, v147
	v_fmamk_f32 v146, v146, 0x3b2aaaab, v218
	v_cmp_gt_f32_e32 vcc, s71, v146
	v_mul_f32_e32 v147, 0x4b800000, v146
	s_nop 0
	v_cndmask_b32_e32 v146, v146, v147, vcc
	v_rsq_f32_e32 v146, v146
	s_nop 0
	v_mul_f32_e32 v147, 0x45800000, v146
	v_cndmask_b32_e32 v146, v146, v147, vcc
	v_mad_i64_i32 v[148:149], s[8:9], v135, s70, v[8:9]
	v_mul_f32_e32 v147, v102, v146
	v_mul_f32_e32 v147, v124, v147
	v_cvt_pk_bf16_f32 v147, v147, v147
	global_store_short_d16_hi v[148:149], v147, off
	v_mul_f32_e32 v147, v103, v146
	v_mul_f32_e32 v147, v125, v147
	v_cvt_pk_bf16_f32 v147, v147, v147
	global_store_short_d16_hi v[148:149], v147, off offset:128
	v_mul_f32_e32 v147, v104, v146
	v_mul_f32_e32 v147, v126, v147
	v_cvt_pk_bf16_f32 v147, v147, v147
	global_store_short_d16_hi v[148:149], v147, off offset:256
	v_mul_f32_e32 v147, v105, v146
	v_mul_f32_e32 v147, v127, v147
	v_cvt_pk_bf16_f32 v147, v147, v147
	global_store_short_d16_hi v[148:149], v147, off offset:384
	v_mul_f32_e32 v147, v106, v146
	v_mul_f32_e32 v147, v128, v147
	v_cvt_pk_bf16_f32 v147, v147, v147
	global_store_short_d16_hi v[148:149], v147, off offset:512
	v_mul_f32_e32 v147, v107, v146
	v_mul_f32_e32 v147, v129, v147
	v_cvt_pk_bf16_f32 v147, v147, v147
	global_store_short_d16_hi v[148:149], v147, off offset:640
	v_mul_f32_e32 v146, v108, v108
	v_mul_f32_e32 v147, v109, v109
	v_add_f32_e32 v146, v146, v147
	v_mul_f32_e32 v147, v110, v110
	v_add_f32_e32 v146, v146, v147
	v_mul_f32_e32 v147, v111, v111
	v_add_f32_e32 v146, v146, v147
	s_nop 1
	v_add_f32_dpp v146, v146, v146 quad_perm:[1,0,3,2] row_mask:0xf bank_mask:0xf
	s_nop 1
	v_add_f32_dpp v146, v146, v146 quad_perm:[2,3,0,1] row_mask:0xf bank_mask:0xf
	s_nop 1
	v_add_f32_dpp v146, v146, v146 row_half_mirror row_mask:0xf bank_mask:0xf
	s_nop 1
	v_add_f32_dpp v146, v146, v146 row_mirror row_mask:0xf bank_mask:0xf
	v_mov_b32_e32 v147, v146
	s_nop 1
	v_permlane16_swap_b32 v146, v147
	v_add_f32_e32 v146, v146, v147
	v_mov_b32_e32 v147, v146
	s_nop 1
	v_permlane32_swap_b32 v146, v147
	v_add_f32_e32 v146, v146, v147
	v_fmamk_f32 v146, v146, 0x3b800000, v218
	v_cmp_gt_f32_e32 vcc, s71, v146
	v_mul_f32_e32 v147, 0x4b800000, v146
	s_nop 0
	v_cndmask_b32_e32 v146, v146, v147, vcc
	v_rsq_f32_e32 v146, v146
	s_nop 0
	v_mul_f32_e32 v147, 0x45800000, v146
	v_cndmask_b32_e32 v146, v146, v147, vcc
	v_ashrrev_i32_e32 v151, 31, v135
	v_mov_b32_e32 v150, v135
	v_lshlrev_b64 v[148:149], 9, v[150:151]
	v_lshl_add_u64 v[148:149], v[10:11], 0, v[148:149]
	v_lshlrev_b64 v[152:153], 10, v[150:151]
	s_waitcnt lgkmcnt(0)
	v_lshl_add_u64 v[152:153], s[10:11], 0, v[152:153]
	v_lshlrev_b32_e32 v154, 2, v6
	v_mov_b32_e32 v155, v3
	v_lshl_add_u64 v[154:155], v[152:153], 0, v[154:155]
	s_mov_b64 s[8:9], 0x7000000
	v_lshl_add_u64 v[154:155], v[154:155], 0, s[8:9]
	v_mul_f32_e32 v147, v108, v146
	v_mul_f32_e32 v147, v130, v147
	v_cvt_pk_bf16_f32 v150, v147, v147
	global_store_short_d16_hi v[148:149], v150, off
	global_store_dword v[154:155], v147, off
	v_mul_f32_e32 v147, v109, v146
	v_mul_f32_e32 v147, v131, v147
	v_cvt_pk_bf16_f32 v150, v147, v147
	global_store_short_d16_hi v[148:149], v150, off offset:128
	global_store_dword v[154:155], v147, off offset:256
	v_mul_f32_e32 v147, v110, v146
	v_mul_f32_e32 v147, v132, v147
	v_cvt_pk_bf16_f32 v150, v147, v147
	global_store_short_d16_hi v[148:149], v150, off offset:256
	global_store_dword v[154:155], v147, off offset:512
	v_mul_f32_e32 v147, v111, v146
	v_mul_f32_e32 v147, v133, v147
	v_cvt_pk_bf16_f32 v150, v147, v147
	global_store_short_d16_hi v[148:149], v150, off offset:384
	global_store_dword v[154:155], v147, off offset:768
	s_and_saveexec_b64 s[8:9], s[4:5]
	v_cvt_pk_bf16_f32 v147, v112, v112
	global_store_short_d16_hi v[138:139], v147, off offset:1280
	s_movk_i32 s3, 0xfc80
	v_mad_i64_i32 v[148:149], s[12:13], v135, s3, v[152:153]
	v_lshlrev_b32_e32 v150, 2, v6
	v_mov_b32_e32 v151, v3
	v_lshl_add_u64 v[148:149], v[148:149], 0, v[150:151]
	v_add_co_u32_e32 v148, vcc, 0x7400000, v148
	s_nop 1
	v_addc_co_u32_e32 v149, vcc, 0, v149, vcc
	global_store_dword v[148:149], v112, off
	s_or_b64 exec, exec, s[8:9]
	s_waitcnt vmcnt(0)
	v_lshlrev_b32_e32 v188, 16, v188
	v_lshlrev_b32_e32 v199, 16, v199
	v_add_f32_e32 v188, v188, v199
	v_lshlrev_b32_e32 v189, 16, v189
	v_lshlrev_b32_e32 v200, 16, v200
	v_add_f32_e32 v189, v189, v200
	v_lshlrev_b32_e32 v190, 16, v190
	v_lshlrev_b32_e32 v201, 16, v201
	v_add_f32_e32 v190, v190, v201
	v_lshlrev_b32_e32 v191, 16, v191
	v_lshlrev_b32_e32 v202, 16, v202
	v_add_f32_e32 v191, v191, v202
	v_lshlrev_b32_e32 v192, 16, v192
	v_lshlrev_b32_e32 v203, 16, v203
	v_add_f32_e32 v192, v192, v203
	v_lshlrev_b32_e32 v193, 16, v193
	v_lshlrev_b32_e32 v204, 16, v204
	v_add_f32_e32 v193, v193, v204
	v_lshlrev_b32_e32 v194, 16, v194
	v_lshlrev_b32_e32 v205, 16, v205
	v_add_f32_e32 v194, v194, v205
	v_lshlrev_b32_e32 v195, 16, v195
	v_lshlrev_b32_e32 v206, 16, v206
	v_add_f32_e32 v195, v195, v206
	v_lshlrev_b32_e32 v196, 16, v196
	v_lshlrev_b32_e32 v207, 16, v207
	v_add_f32_e32 v196, v196, v207
	v_lshlrev_b32_e32 v197, 16, v197
	v_lshlrev_b32_e32 v208, 16, v208
	v_add_f32_e32 v197, v197, v208
	v_lshlrev_b32_e32 v198, 16, v198
	v_lshlrev_b32_e32 v209, 16, v209
	v_add_f32_e32 v198, v209, v198
	v_mul_f32_e32 v146, v189, v189
	v_fmac_f32_e32 v146, v188, v188
	v_mul_f32_e32 v147, v190, v190
	v_add_f32_e32 v146, v146, v147
	v_mul_f32_e32 v147, v191, v191
	v_add_f32_e32 v146, v146, v147
	v_mul_f32_e32 v147, v192, v192
	v_add_f32_e32 v146, v146, v147
	v_mul_f32_e32 v147, v193, v193
	v_add_f32_e32 v146, v146, v147
	s_nop 1
	v_add_f32_dpp v146, v146, v146 quad_perm:[1,0,3,2] row_mask:0xf bank_mask:0xf
	s_nop 1
	v_add_f32_dpp v146, v146, v146 quad_perm:[2,3,0,1] row_mask:0xf bank_mask:0xf
	s_nop 1
	v_add_f32_dpp v146, v146, v146 row_half_mirror row_mask:0xf bank_mask:0xf
	s_nop 1
	v_add_f32_dpp v146, v146, v146 row_mirror row_mask:0xf bank_mask:0xf
	v_mov_b32_e32 v147, v146
	s_nop 1
	v_permlane16_swap_b32 v146, v147
	v_add_f32_e32 v146, v146, v147
	v_mov_b32_e32 v147, v146
	s_nop 1
	v_permlane32_swap_b32 v146, v147
	v_add_f32_e32 v146, v146, v147
	v_fmamk_f32 v146, v146, 0x3b2aaaab, v218
	v_cmp_gt_f32_e32 vcc, s71, v146
	v_mul_f32_e32 v147, 0x4b800000, v146
	s_nop 0
	v_cndmask_b32_e32 v146, v146, v147, vcc
	v_rsq_f32_e32 v146, v146
	s_nop 0
	v_mul_f32_e32 v147, 0x45800000, v146
	v_cndmask_b32_e32 v146, v146, v147, vcc
	v_mad_i64_i32 v[148:149], s[8:9], v248, s70, v[8:9]
	v_mul_f32_e32 v147, v188, v146
	v_mul_f32_e32 v147, v124, v147
	v_cvt_pk_bf16_f32 v147, v147, v147
	global_store_short_d16_hi v[148:149], v147, off
	v_mul_f32_e32 v147, v189, v146
	v_mul_f32_e32 v147, v125, v147
	v_cvt_pk_bf16_f32 v147, v147, v147
	global_store_short_d16_hi v[148:149], v147, off offset:128
	v_mul_f32_e32 v147, v190, v146
	v_mul_f32_e32 v147, v126, v147
	v_cvt_pk_bf16_f32 v147, v147, v147
	global_store_short_d16_hi v[148:149], v147, off offset:256
	v_mul_f32_e32 v147, v191, v146
	v_mul_f32_e32 v147, v127, v147
	v_cvt_pk_bf16_f32 v147, v147, v147
	global_store_short_d16_hi v[148:149], v147, off offset:384
	v_mul_f32_e32 v147, v192, v146
	v_mul_f32_e32 v147, v128, v147
	v_cvt_pk_bf16_f32 v147, v147, v147
	global_store_short_d16_hi v[148:149], v147, off offset:512
	v_mul_f32_e32 v147, v193, v146
	v_mul_f32_e32 v147, v129, v147
	v_cvt_pk_bf16_f32 v147, v147, v147
	global_store_short_d16_hi v[148:149], v147, off offset:640
	v_mul_f32_e32 v146, v194, v194
	v_mul_f32_e32 v147, v195, v195
	v_add_f32_e32 v146, v146, v147
	v_mul_f32_e32 v147, v196, v196
	v_add_f32_e32 v146, v146, v147
	v_mul_f32_e32 v147, v197, v197
	v_add_f32_e32 v146, v146, v147
	s_nop 1
	v_add_f32_dpp v146, v146, v146 quad_perm:[1,0,3,2] row_mask:0xf bank_mask:0xf
	s_nop 1
	v_add_f32_dpp v146, v146, v146 quad_perm:[2,3,0,1] row_mask:0xf bank_mask:0xf
	s_nop 1
	v_add_f32_dpp v146, v146, v146 row_half_mirror row_mask:0xf bank_mask:0xf
	s_nop 1
	v_add_f32_dpp v146, v146, v146 row_mirror row_mask:0xf bank_mask:0xf
	v_mov_b32_e32 v147, v146
	s_nop 1
	v_permlane16_swap_b32 v146, v147
	v_add_f32_e32 v146, v146, v147
	v_mov_b32_e32 v147, v146
	s_nop 1
	v_permlane32_swap_b32 v146, v147
	v_add_f32_e32 v146, v146, v147
	v_fmamk_f32 v146, v146, 0x3b800000, v218
	v_cmp_gt_f32_e32 vcc, s71, v146
	v_mul_f32_e32 v147, 0x4b800000, v146
	s_nop 0
	v_cndmask_b32_e32 v146, v146, v147, vcc
	v_rsq_f32_e32 v146, v146
	s_nop 0
	v_mul_f32_e32 v147, 0x45800000, v146
	v_cndmask_b32_e32 v146, v146, v147, vcc
	v_ashrrev_i32_e32 v151, 31, v248
	v_mov_b32_e32 v150, v248
	v_lshlrev_b64 v[148:149], 9, v[150:151]
	v_lshl_add_u64 v[148:149], v[10:11], 0, v[148:149]
	v_mul_f32_e32 v147, v194, v146
	v_mul_f32_e32 v147, v130, v147
	v_cvt_pk_bf16_f32 v150, v147, v147
	global_store_short_d16_hi v[148:149], v150, off
	v_mul_f32_e32 v147, v195, v146
	v_mul_f32_e32 v147, v131, v147
	v_cvt_pk_bf16_f32 v150, v147, v147
	global_store_short_d16_hi v[148:149], v150, off offset:128
	v_mul_f32_e32 v147, v196, v146
	v_mul_f32_e32 v147, v132, v147
	v_cvt_pk_bf16_f32 v150, v147, v147
	global_store_short_d16_hi v[148:149], v150, off offset:256
	v_mul_f32_e32 v147, v197, v146
	v_mul_f32_e32 v147, v133, v147
	v_cvt_pk_bf16_f32 v150, v147, v147
	global_store_short_d16_hi v[148:149], v150, off offset:384
	s_and_saveexec_b64 s[8:9], s[4:5]
	v_cvt_pk_bf16_f32 v147, v198, v198
	global_store_short_d16_hi v[250:251], v147, off offset:1280
	s_or_b64 exec, exec, s[8:9]
	v_lshlrev_b32_e32 v210, 16, v210
	v_lshlrev_b32_e32 v237, 16, v237
	v_add_f32_e32 v210, v210, v237
	v_lshlrev_b32_e32 v211, 16, v211
	v_lshlrev_b32_e32 v238, 16, v238
	v_add_f32_e32 v211, v211, v238
	v_lshlrev_b32_e32 v212, 16, v212
	v_lshlrev_b32_e32 v239, 16, v239
	v_add_f32_e32 v212, v212, v239
	v_lshlrev_b32_e32 v213, 16, v213
	v_lshlrev_b32_e32 v240, 16, v240
	v_add_f32_e32 v213, v213, v240
	v_lshlrev_b32_e32 v214, 16, v214
	v_lshlrev_b32_e32 v241, 16, v241
	v_add_f32_e32 v214, v214, v241
	v_lshlrev_b32_e32 v215, 16, v215
	v_lshlrev_b32_e32 v242, 16, v242
	v_add_f32_e32 v215, v215, v242
	v_lshlrev_b32_e32 v216, 16, v216
	v_lshlrev_b32_e32 v243, 16, v243
	v_add_f32_e32 v216, v216, v243
	v_lshlrev_b32_e32 v217, 16, v217
	v_lshlrev_b32_e32 v244, 16, v244
	v_add_f32_e32 v217, v217, v244
	v_lshlrev_b32_e32 v234, 16, v234
	v_lshlrev_b32_e32 v245, 16, v245
	v_add_f32_e32 v234, v234, v245
	v_lshlrev_b32_e32 v235, 16, v235
	v_lshlrev_b32_e32 v246, 16, v246
	v_add_f32_e32 v235, v235, v246
	v_lshlrev_b32_e32 v236, 16, v236
	v_lshlrev_b32_e32 v247, 16, v247
	v_add_f32_e32 v236, v247, v236
	v_mul_f32_e32 v146, v211, v211
	v_fmac_f32_e32 v146, v210, v210
	v_mul_f32_e32 v147, v212, v212
	v_add_f32_e32 v146, v146, v147
	v_mul_f32_e32 v147, v213, v213
	v_add_f32_e32 v146, v146, v147
	v_mul_f32_e32 v147, v214, v214
	v_add_f32_e32 v146, v146, v147
	v_mul_f32_e32 v147, v215, v215
	v_add_f32_e32 v146, v146, v147
	s_nop 1
	v_add_f32_dpp v146, v146, v146 quad_perm:[1,0,3,2] row_mask:0xf bank_mask:0xf
	s_nop 1
	v_add_f32_dpp v146, v146, v146 quad_perm:[2,3,0,1] row_mask:0xf bank_mask:0xf
	s_nop 1
	v_add_f32_dpp v146, v146, v146 row_half_mirror row_mask:0xf bank_mask:0xf
	s_nop 1
	v_add_f32_dpp v146, v146, v146 row_mirror row_mask:0xf bank_mask:0xf
	v_mov_b32_e32 v147, v146
	s_nop 1
	v_permlane16_swap_b32 v146, v147
	v_add_f32_e32 v146, v146, v147
	v_mov_b32_e32 v147, v146
	s_nop 1
	v_permlane32_swap_b32 v146, v147
	v_add_f32_e32 v146, v146, v147
	v_fmamk_f32 v146, v146, 0x3b2aaaab, v218
	v_cmp_gt_f32_e32 vcc, s71, v146
	v_mul_f32_e32 v147, 0x4b800000, v146
	s_nop 0
	v_cndmask_b32_e32 v146, v146, v147, vcc
	v_rsq_f32_e32 v146, v146
	s_nop 0
	v_mul_f32_e32 v147, 0x45800000, v146
	v_cndmask_b32_e32 v146, v146, v147, vcc
	v_mad_i64_i32 v[148:149], s[8:9], v249, s70, v[8:9]
	v_mul_f32_e32 v147, v210, v146
	v_mul_f32_e32 v147, v124, v147
	v_cvt_pk_bf16_f32 v147, v147, v147
	global_store_short_d16_hi v[148:149], v147, off
	v_mul_f32_e32 v147, v211, v146
	v_mul_f32_e32 v147, v125, v147
	v_cvt_pk_bf16_f32 v147, v147, v147
	global_store_short_d16_hi v[148:149], v147, off offset:128
	v_mul_f32_e32 v147, v212, v146
	v_mul_f32_e32 v147, v126, v147
	v_cvt_pk_bf16_f32 v147, v147, v147
	global_store_short_d16_hi v[148:149], v147, off offset:256
	v_mul_f32_e32 v147, v213, v146
	v_mul_f32_e32 v147, v127, v147
	v_cvt_pk_bf16_f32 v147, v147, v147
	global_store_short_d16_hi v[148:149], v147, off offset:384
	v_mul_f32_e32 v147, v214, v146
	v_mul_f32_e32 v147, v128, v147
	v_cvt_pk_bf16_f32 v147, v147, v147
	global_store_short_d16_hi v[148:149], v147, off offset:512
	v_mul_f32_e32 v147, v215, v146
	v_mul_f32_e32 v147, v129, v147
	v_cvt_pk_bf16_f32 v147, v147, v147
	global_store_short_d16_hi v[148:149], v147, off offset:640
	v_mul_f32_e32 v146, v216, v216
	v_mul_f32_e32 v147, v217, v217
	v_add_f32_e32 v146, v146, v147
	v_mul_f32_e32 v147, v234, v234
	v_add_f32_e32 v146, v146, v147
	v_mul_f32_e32 v147, v235, v235
	v_add_f32_e32 v146, v146, v147
	s_nop 1
	v_add_f32_dpp v146, v146, v146 quad_perm:[1,0,3,2] row_mask:0xf bank_mask:0xf
	s_nop 1
	v_add_f32_dpp v146, v146, v146 quad_perm:[2,3,0,1] row_mask:0xf bank_mask:0xf
	s_nop 1
	v_add_f32_dpp v146, v146, v146 row_half_mirror row_mask:0xf bank_mask:0xf
	s_nop 1
	v_add_f32_dpp v146, v146, v146 row_mirror row_mask:0xf bank_mask:0xf
	v_mov_b32_e32 v147, v146
	s_nop 1
	v_permlane16_swap_b32 v146, v147
	v_add_f32_e32 v146, v146, v147
	v_mov_b32_e32 v147, v146
	s_nop 1
	v_permlane32_swap_b32 v146, v147
	v_add_f32_e32 v146, v146, v147
	v_fmamk_f32 v146, v146, 0x3b800000, v218
	v_cmp_gt_f32_e32 vcc, s71, v146
	v_mul_f32_e32 v147, 0x4b800000, v146
	s_nop 0
	v_cndmask_b32_e32 v146, v146, v147, vcc
	v_rsq_f32_e32 v146, v146
	s_nop 0
	v_mul_f32_e32 v147, 0x45800000, v146
	v_cndmask_b32_e32 v146, v146, v147, vcc
	v_ashrrev_i32_e32 v151, 31, v249
	v_mov_b32_e32 v150, v249
	v_lshlrev_b64 v[148:149], 9, v[150:151]
	v_lshl_add_u64 v[148:149], v[10:11], 0, v[148:149]
	v_mul_f32_e32 v147, v216, v146
	v_mul_f32_e32 v147, v130, v147
	v_cvt_pk_bf16_f32 v150, v147, v147
	global_store_short_d16_hi v[148:149], v150, off
	v_mul_f32_e32 v147, v217, v146
	v_mul_f32_e32 v147, v131, v147
	v_cvt_pk_bf16_f32 v150, v147, v147
	global_store_short_d16_hi v[148:149], v150, off offset:128
	v_mul_f32_e32 v147, v234, v146
	v_mul_f32_e32 v147, v132, v147
	v_cvt_pk_bf16_f32 v150, v147, v147
	global_store_short_d16_hi v[148:149], v150, off offset:256
	v_mul_f32_e32 v147, v235, v146
	v_mul_f32_e32 v147, v133, v147
	v_cvt_pk_bf16_f32 v150, v147, v147
	global_store_short_d16_hi v[148:149], v150, off offset:384
	s_and_saveexec_b64 s[8:9], s[4:5]
	v_cvt_pk_bf16_f32 v147, v236, v236
	global_store_short_d16_hi v[252:253], v147, off offset:1280
	s_or_b64 exec, exec, s[8:9]
	s_branch .LBB0_711
